# attention-phase setup: 40 serialized rel_bias loads prefetched in one batch; on top of batched/coalesced GEMM epilogue loads
# speedup vs baseline: 1.0299x; 1.0079x over previous
; #define GAS __attribute__((address_space(1)))
; #define LAS __attribute__((address_space(3)))
; #define LAS __attribute__((address_space(3)))
; __device__ __forceinline__ void attn_phase(const AttnArgs& A, GAS unsigned* counters, LAS unsigned char* lds) {
;     LAS unsigned* bc = (LAS unsigned*)(lds + BC_OFF);
;     if (threadIdx.x < 64) {
;         LAS float* prm = (LAS float*)(lds + PRM_OFF); const int ln = threadIdx.x;
;         const GAS float* lq = A.lambda_qk; const float s1 = wave_sum(lq[ln] * lq[64 + ln]), s2 = wave_sum(lq[128 + ln] * lq[192 + ln]);
;         const float gb = A.qk_g_diff[ln] * A.qk_g_diff[64 + ln], gc = A.qk_g_ch[ln] * A.qk_g_ch[64 + ln]; float gmb = fabsf(gb), gmc = fabsf(gc);
; #pragma unroll
;         for (int o_ = 1; o_ < 64; o_ <<= 1) { gmb = fmaxf(gmb, __shfl_xor(gmb, o_)); gmc = fmaxf(gmc, __shfl_xor(gmc, o_)); }
;         prm[32 + ln] = gb; prm[96 + ln] = gc; prm[160 + ln] = A.subln_g[ln] * (1.0f - A.lam_init); prm[224 + ln] = A.subln_g[64 + ln] * (1.0f - A.lam_init);
;         const float M0c = 8.0f * gmc * LOG2E * 1.02f;
;         if (ln == 0) { prm[0] = __expf(s1) - __expf(s2) + A.lam_init; prm[1] = 8.0f * gmb * LOG2E * 1.02f; }
;         for (int hc = 0; hc < 8; ++hc) { float bmx = -3.0e38f, bmn = 3.0e38f;
;             for (int j = ln; j < 257; j += 64) { const float v = A.rel_bias[hc * 257 + j]; bmx = fmaxf(bmx, v); bmn = fminf(bmn, v); }
; #pragma unroll
;             for (int o_ = 1; o_ < 64; o_ <<= 1) { bmx = fmaxf(bmx, __shfl_xor(bmx, o_)); bmn = fminf(bmn, __shfl_xor(bmn, o_)); }
;             if (ln == 0) { prm[2 + hc] = M0c + bmx * LOG2E; prm[10 + hc] = (2.0f * M0c + (bmx - bmn) * LOG2E < 100.0f) ? 1.0f : 0.0f; } }
.LBB0_313:
	s_or_b64 exec, exec, s[2:3]
	v_add_u32_e32 v232, 64, v242
	v_mov_b32_e32 v230, 0x300
	v_mov_b32_e32 v233, 0x400
	v_mov_b32_e32 v231, 0
	v_cmp_eq_u32_e32 vcc, 0, v232
	s_nop 1
	v_cndmask_b32_e32 v230, v230, v233, vcc
	v_lshl_add_u64 v[226:227], s[4:5], 0, v[190:191]
	global_load_dword v130, v[226:227], off
	global_load_dword v131, v[226:227], off offset:256
	global_load_dword v132, v[226:227], off offset:512
	global_load_dword v133, v[226:227], off offset:768
	v_lshl_add_u64 v[228:229], v[226:227], 0, v[230:231]
	global_load_dword v134, v[228:229], off
	v_lshl_add_u64 v[226:227], s[4:5], 0, v[168:169]
	global_load_dword v135, v[226:227], off
	global_load_dword v136, v[226:227], off offset:256
	global_load_dword v137, v[226:227], off offset:512
	global_load_dword v138, v[226:227], off offset:768
	v_lshl_add_u64 v[228:229], v[226:227], 0, v[230:231]
	global_load_dword v139, v[228:229], off
	v_lshl_add_u64 v[226:227], s[4:5], 0, v[170:171]
	global_load_dword v140, v[226:227], off
	global_load_dword v141, v[226:227], off offset:256
	global_load_dword v142, v[226:227], off offset:512
	global_load_dword v143, v[226:227], off offset:768
	v_lshl_add_u64 v[228:229], v[226:227], 0, v[230:231]
	global_load_dword v144, v[228:229], off
	v_lshl_add_u64 v[226:227], s[4:5], 0, v[172:173]
	global_load_dword v145, v[226:227], off
	global_load_dword v146, v[226:227], off offset:256
	global_load_dword v147, v[226:227], off offset:512
	global_load_dword v148, v[226:227], off offset:768
	v_lshl_add_u64 v[228:229], v[226:227], 0, v[230:231]
	global_load_dword v149, v[228:229], off
	v_lshl_add_u64 v[226:227], s[4:5], 0, v[174:175]
	global_load_dword v206, v[226:227], off
	global_load_dword v207, v[226:227], off offset:256
	global_load_dword v208, v[226:227], off offset:512
	global_load_dword v209, v[226:227], off offset:768
	v_lshl_add_u64 v[228:229], v[226:227], 0, v[230:231]
	global_load_dword v210, v[228:229], off
	v_lshl_add_u64 v[226:227], s[4:5], 0, v[176:177]
	global_load_dword v211, v[226:227], off
	global_load_dword v212, v[226:227], off offset:256
	global_load_dword v213, v[226:227], off offset:512
	global_load_dword v214, v[226:227], off offset:768
	v_lshl_add_u64 v[228:229], v[226:227], 0, v[230:231]
	global_load_dword v215, v[228:229], off
	v_lshl_add_u64 v[226:227], s[4:5], 0, v[178:179]
	global_load_dword v216, v[226:227], off
	global_load_dword v217, v[226:227], off offset:256
	global_load_dword v218, v[226:227], off offset:512
	global_load_dword v219, v[226:227], off offset:768
	v_lshl_add_u64 v[228:229], v[226:227], 0, v[230:231]
	global_load_dword v220, v[228:229], off
	v_lshl_add_u64 v[226:227], s[4:5], 0, v[180:181]
	global_load_dword v221, v[226:227], off
	global_load_dword v222, v[226:227], off offset:256
	global_load_dword v223, v[226:227], off offset:512
	global_load_dword v224, v[226:227], off offset:768
	v_lshl_add_u64 v[228:229], v[226:227], 0, v[230:231]
	global_load_dword v225, v[228:229], off
	s_waitcnt vmcnt(0)
	v_lshl_add_u64 v[2:3], s[4:5], 0, v[190:191]
	v_mov_b32_e32 v11, 0x7f61b1e6
	v_mov_b32_e32 v14, 0xff61b1e6
	s_mov_b64 s[2:3], 0
	v_mov_b32_e32 v9, v242
	s_mov_b64 s[16:17], 0x100
.LBB0_314:
	v_max_f32_e32 v10, v130, v130
	v_max_f32_e32 v14, v14, v10
	v_min_f32_e32 v11, v11, v10
	v_max_f32_e32 v10, v131, v131
	v_max_f32_e32 v14, v14, v10
	v_min_f32_e32 v11, v11, v10
	v_max_f32_e32 v10, v132, v132
	v_max_f32_e32 v14, v14, v10
	v_min_f32_e32 v11, v11, v10
	v_max_f32_e32 v10, v133, v133
	v_max_f32_e32 v14, v14, v10
	v_min_f32_e32 v11, v11, v10
	v_max_f32_e32 v10, v134, v134
	v_max_f32_e32 v14, v14, v10
	v_min_f32_e32 v11, v11, v10
	s_or_b64 exec, exec, s[2:3]
	s_waitcnt lgkmcnt(1)
	v_max_f32_e32 v2, v13, v13
	v_max_f32_e32 v3, v12, v12
	v_max_f32_e32 v2, v3, v2
	v_mul_f32_e32 v2, 0x41000000, v2
	v_mul_f32_e32 v2, 0x3fb8aa3b, v2
	v_mul_f32_e32 v9, 0x3f828f5c, v2
	ds_bpermute_b32 v2, v8, v14
	v_max_f32_e32 v3, v14, v14
	v_add_f32_e32 v10, v9, v9
	s_waitcnt lgkmcnt(0)
	v_max_f32_e32 v2, v2, v2
	v_max_f32_e32 v2, v3, v2
	ds_bpermute_b32 v3, v8, v11
	v_max_f32_e32 v11, v11, v11
	s_waitcnt lgkmcnt(0)
	v_max_f32_e32 v3, v3, v3
	v_min_f32_e32 v3, v11, v3
	ds_bpermute_b32 v11, v7, v2
	s_waitcnt lgkmcnt(0)
	v_max_f32_e32 v11, v11, v11
	v_max_f32_e32 v2, v2, v11
	ds_bpermute_b32 v11, v7, v3
	s_waitcnt lgkmcnt(0)
	v_max_f32_e32 v11, v11, v11
	v_min_f32_e32 v3, v3, v11
	ds_bpermute_b32 v11, v6, v2
	s_waitcnt lgkmcnt(0)
	v_max_f32_e32 v11, v11, v11
	v_max_f32_e32 v2, v2, v11
	ds_bpermute_b32 v11, v6, v3
	s_waitcnt lgkmcnt(0)
	v_max_f32_e32 v11, v11, v11
	v_min_f32_e32 v3, v3, v11
	ds_bpermute_b32 v11, v5, v2
	s_waitcnt lgkmcnt(0)
	v_max_f32_e32 v11, v11, v11
	v_max_f32_e32 v2, v2, v11
	ds_bpermute_b32 v11, v5, v3
	s_waitcnt lgkmcnt(0)
	v_max_f32_e32 v11, v11, v11
	v_min_f32_e32 v3, v3, v11
	ds_bpermute_b32 v11, v0, v2
	s_waitcnt lgkmcnt(0)
	v_max_f32_e32 v11, v11, v11
	v_max_f32_e32 v2, v2, v11
	ds_bpermute_b32 v11, v0, v3
	s_waitcnt lgkmcnt(0)
	v_max_f32_e32 v11, v11, v11
	v_min_f32_e32 v11, v3, v11
	ds_bpermute_b32 v3, v4, v2
	ds_bpermute_b32 v12, v4, v11
	s_and_saveexec_b64 s[2:3], s[66:67]
	s_cbranch_execz .LBB0_317
	s_waitcnt lgkmcnt(0)
	v_max_f32_e32 v12, v12, v12
	v_max_f32_e32 v11, v11, v11
	v_max_f32_e32 v3, v3, v3
	v_max_f32_e32 v2, v2, v2
	v_min_f32_e32 v11, v11, v12
	v_max_f32_e32 v2, v2, v3
	v_sub_f32_e32 v3, v2, v11
	v_fmamk_f32 v3, v3, 0x3fb8aa3b, v10
	v_readlane_b32 s6, v254, 2
	v_cmp_gt_f32_e32 vcc, s24, v3
	v_fmamk_f32 v2, v2, 0x3fb8aa3b, v9
	v_mov_b32_e32 v11, s6
	v_readlane_b32 s6, v254, 3
	v_cndmask_b32_e64 v3, 0, 1.0, vcc
	ds_write_b32 v11, v2
	v_mov_b32_e32 v2, s6
	ds_write_b32 v2, v3

; __device__ __forceinline__ void attn_phase(const AttnArgs& A, GAS unsigned* counters, LAS unsigned char* lds) {
;     ...
;         for (int hc = 0; hc < 8; ++hc) { float bmx = -3.0e38f, bmn = 3.0e38f;
;             for (int j = ln; j < 257; j += 64) { const float v = A.rel_bias[hc * 257 + j]; bmx = fmaxf(bmx, v); bmn = fminf(bmn, v); }
; #pragma unroll
;             for (int o_ = 1; o_ < 64; o_ <<= 1) { bmx = fmaxf(bmx, __shfl_xor(bmx, o_)); bmn = fminf(bmn, __shfl_xor(bmn, o_)); }
;             if (ln == 0) { prm[2 + hc] = M0c + bmx * LOG2E; prm[10 + hc] = (2.0f * M0c + (bmx - bmn) * LOG2E < 100.0f) ? 1.0f : 0.0f; } }
.LBB0_318:
	v_max_f32_e32 v14, v135, v135
	v_max_f32_e32 v13, v13, v14
	v_min_f32_e32 v11, v11, v14
	v_max_f32_e32 v14, v136, v136
	v_max_f32_e32 v13, v13, v14
	v_min_f32_e32 v11, v11, v14
	v_max_f32_e32 v14, v137, v137
	v_max_f32_e32 v13, v13, v14
	v_min_f32_e32 v11, v11, v14
	v_max_f32_e32 v14, v138, v138
	v_max_f32_e32 v13, v13, v14
	v_min_f32_e32 v11, v11, v14
	v_max_f32_e32 v14, v139, v139
	v_max_f32_e32 v13, v13, v14
	v_min_f32_e32 v11, v11, v14
	s_or_b64 exec, exec, s[2:3]
	ds_bpermute_b32 v2, v8, v13
	v_max_f32_e32 v3, v13, v13
	s_waitcnt lgkmcnt(0)
	v_max_f32_e32 v2, v2, v2
	v_max_f32_e32 v2, v3, v2
	ds_bpermute_b32 v3, v8, v11
	v_max_f32_e32 v11, v11, v11
	s_waitcnt lgkmcnt(0)
	v_max_f32_e32 v3, v3, v3
	v_min_f32_e32 v3, v11, v3
	ds_bpermute_b32 v11, v7, v2
	s_waitcnt lgkmcnt(0)
	v_max_f32_e32 v11, v11, v11
	v_max_f32_e32 v2, v2, v11
	ds_bpermute_b32 v11, v7, v3
	s_waitcnt lgkmcnt(0)
	v_max_f32_e32 v11, v11, v11
	v_min_f32_e32 v3, v3, v11
	ds_bpermute_b32 v11, v6, v2
	s_waitcnt lgkmcnt(0)
	v_max_f32_e32 v11, v11, v11
	v_max_f32_e32 v2, v2, v11
	ds_bpermute_b32 v11, v6, v3
	s_waitcnt lgkmcnt(0)
	v_max_f32_e32 v11, v11, v11
	v_min_f32_e32 v3, v3, v11
	ds_bpermute_b32 v11, v5, v2
	s_waitcnt lgkmcnt(0)
	v_max_f32_e32 v11, v11, v11
	v_max_f32_e32 v2, v2, v11
	ds_bpermute_b32 v11, v5, v3
	s_waitcnt lgkmcnt(0)
	v_max_f32_e32 v11, v11, v11
	v_min_f32_e32 v3, v3, v11
	ds_bpermute_b32 v11, v0, v2
	s_waitcnt lgkmcnt(0)
	v_max_f32_e32 v11, v11, v11
	v_max_f32_e32 v2, v2, v11
	ds_bpermute_b32 v11, v0, v3
	s_waitcnt lgkmcnt(0)
	v_max_f32_e32 v11, v11, v11
	v_min_f32_e32 v11, v3, v11
	ds_bpermute_b32 v3, v4, v2
	ds_bpermute_b32 v12, v4, v11
	s_and_saveexec_b64 s[2:3], s[66:67]
	s_cbranch_execz .LBB0_321
	s_waitcnt lgkmcnt(0)
	v_max_f32_e32 v12, v12, v12
	v_max_f32_e32 v11, v11, v11
	v_max_f32_e32 v3, v3, v3
	v_max_f32_e32 v2, v2, v2
	v_min_f32_e32 v11, v11, v12
	v_max_f32_e32 v2, v2, v3
	v_sub_f32_e32 v3, v2, v11
	v_fmamk_f32 v3, v3, 0x3fb8aa3b, v10
	v_readlane_b32 s6, v254, 4
	v_cmp_gt_f32_e32 vcc, s24, v3
	v_fmamk_f32 v2, v2, 0x3fb8aa3b, v9
	v_mov_b32_e32 v11, s6
	v_readlane_b32 s6, v254, 5
	v_cndmask_b32_e64 v3, 0, 1.0, vcc
	ds_write_b32 v11, v2
	v_mov_b32_e32 v2, s6
	ds_write_b32 v2, v3

; __device__ __forceinline__ void attn_phase(const AttnArgs& A, GAS unsigned* counters, LAS unsigned char* lds) {
;     ...
;         for (int hc = 0; hc < 8; ++hc) { float bmx = -3.0e38f, bmn = 3.0e38f;
;             for (int j = ln; j < 257; j += 64) { const float v = A.rel_bias[hc * 257 + j]; bmx = fmaxf(bmx, v); bmn = fminf(bmn, v); }
; #pragma unroll
;             for (int o_ = 1; o_ < 64; o_ <<= 1) { bmx = fmaxf(bmx, __shfl_xor(bmx, o_)); bmn = fminf(bmn, __shfl_xor(bmn, o_)); }
;             if (ln == 0) { prm[2 + hc] = M0c + bmx * LOG2E; prm[10 + hc] = (2.0f * M0c + (bmx - bmn) * LOG2E < 100.0f) ? 1.0f : 0.0f; } }
.LBB0_322:
	v_max_f32_e32 v14, v140, v140
	v_max_f32_e32 v13, v13, v14
	v_min_f32_e32 v11, v11, v14
	v_max_f32_e32 v14, v141, v141
	v_max_f32_e32 v13, v13, v14
	v_min_f32_e32 v11, v11, v14
	v_max_f32_e32 v14, v142, v142
	v_max_f32_e32 v13, v13, v14
	v_min_f32_e32 v11, v11, v14
	v_max_f32_e32 v14, v143, v143
	v_max_f32_e32 v13, v13, v14
	v_min_f32_e32 v11, v11, v14
	v_max_f32_e32 v14, v144, v144
	v_max_f32_e32 v13, v13, v14
	v_min_f32_e32 v11, v11, v14
	s_or_b64 exec, exec, s[2:3]
	ds_bpermute_b32 v2, v8, v13
	v_max_f32_e32 v3, v13, v13
	s_waitcnt lgkmcnt(0)
	v_max_f32_e32 v2, v2, v2
	v_max_f32_e32 v2, v3, v2
	ds_bpermute_b32 v3, v8, v11
	v_max_f32_e32 v11, v11, v11
	s_waitcnt lgkmcnt(0)
	v_max_f32_e32 v3, v3, v3
	v_min_f32_e32 v3, v11, v3
	ds_bpermute_b32 v11, v7, v2
	s_waitcnt lgkmcnt(0)
	v_max_f32_e32 v11, v11, v11
	v_max_f32_e32 v2, v2, v11
	ds_bpermute_b32 v11, v7, v3
	s_waitcnt lgkmcnt(0)
	v_max_f32_e32 v11, v11, v11
	v_min_f32_e32 v3, v3, v11
	ds_bpermute_b32 v11, v6, v2
	s_waitcnt lgkmcnt(0)
	v_max_f32_e32 v11, v11, v11
	v_max_f32_e32 v2, v2, v11
	ds_bpermute_b32 v11, v6, v3
	s_waitcnt lgkmcnt(0)
	v_max_f32_e32 v11, v11, v11
	v_min_f32_e32 v3, v3, v11
	ds_bpermute_b32 v11, v5, v2
	s_waitcnt lgkmcnt(0)
	v_max_f32_e32 v11, v11, v11
	v_max_f32_e32 v2, v2, v11
	ds_bpermute_b32 v11, v5, v3
	s_waitcnt lgkmcnt(0)
	v_max_f32_e32 v11, v11, v11
	v_min_f32_e32 v3, v3, v11
	ds_bpermute_b32 v11, v0, v2
	s_waitcnt lgkmcnt(0)
	v_max_f32_e32 v11, v11, v11
	v_max_f32_e32 v2, v2, v11
	ds_bpermute_b32 v11, v0, v3
	s_waitcnt lgkmcnt(0)
	v_max_f32_e32 v11, v11, v11
	v_min_f32_e32 v11, v3, v11
	ds_bpermute_b32 v3, v4, v2
	ds_bpermute_b32 v12, v4, v11
	s_and_saveexec_b64 s[2:3], s[66:67]
	s_cbranch_execz .LBB0_325
	s_waitcnt lgkmcnt(0)
	v_max_f32_e32 v12, v12, v12
	v_max_f32_e32 v11, v11, v11
	v_max_f32_e32 v3, v3, v3
	v_max_f32_e32 v2, v2, v2
	v_min_f32_e32 v11, v11, v12
	v_max_f32_e32 v2, v2, v3
	v_sub_f32_e32 v3, v2, v11
	v_fmamk_f32 v3, v3, 0x3fb8aa3b, v10
	v_readlane_b32 s6, v254, 6
	v_cmp_gt_f32_e32 vcc, s24, v3
	v_fmamk_f32 v2, v2, 0x3fb8aa3b, v9
	v_mov_b32_e32 v11, s6
	v_readlane_b32 s6, v254, 7
	v_cndmask_b32_e64 v3, 0, 1.0, vcc
	ds_write_b32 v11, v2
	v_mov_b32_e32 v2, s6
	ds_write_b32 v2, v3

; __device__ __forceinline__ void attn_phase(const AttnArgs& A, GAS unsigned* counters, LAS unsigned char* lds) {
;     ...
;         for (int hc = 0; hc < 8; ++hc) { float bmx = -3.0e38f, bmn = 3.0e38f;
;             for (int j = ln; j < 257; j += 64) { const float v = A.rel_bias[hc * 257 + j]; bmx = fmaxf(bmx, v); bmn = fminf(bmn, v); }
; #pragma unroll
;             for (int o_ = 1; o_ < 64; o_ <<= 1) { bmx = fmaxf(bmx, __shfl_xor(bmx, o_)); bmn = fminf(bmn, __shfl_xor(bmn, o_)); }
;             if (ln == 0) { prm[2 + hc] = M0c + bmx * LOG2E; prm[10 + hc] = (2.0f * M0c + (bmx - bmn) * LOG2E < 100.0f) ? 1.0f : 0.0f; } }
.LBB0_326:
	v_max_f32_e32 v14, v145, v145
	v_max_f32_e32 v13, v13, v14
	v_min_f32_e32 v11, v11, v14
	v_max_f32_e32 v14, v146, v146
	v_max_f32_e32 v13, v13, v14
	v_min_f32_e32 v11, v11, v14
	v_max_f32_e32 v14, v147, v147
	v_max_f32_e32 v13, v13, v14
	v_min_f32_e32 v11, v11, v14
	v_max_f32_e32 v14, v148, v148
	v_max_f32_e32 v13, v13, v14
	v_min_f32_e32 v11, v11, v14
	v_max_f32_e32 v14, v149, v149
	v_max_f32_e32 v13, v13, v14
	v_min_f32_e32 v11, v11, v14
	s_or_b64 exec, exec, s[2:3]
	ds_bpermute_b32 v2, v8, v13
	v_max_f32_e32 v3, v13, v13
	s_waitcnt lgkmcnt(0)
	v_max_f32_e32 v2, v2, v2
	v_max_f32_e32 v2, v3, v2
	ds_bpermute_b32 v3, v8, v11
	v_max_f32_e32 v11, v11, v11
	s_waitcnt lgkmcnt(0)
	v_max_f32_e32 v3, v3, v3
	v_min_f32_e32 v3, v11, v3
	ds_bpermute_b32 v11, v7, v2
	s_waitcnt lgkmcnt(0)
	v_max_f32_e32 v11, v11, v11
	v_max_f32_e32 v2, v2, v11
	ds_bpermute_b32 v11, v7, v3
	s_waitcnt lgkmcnt(0)
	v_max_f32_e32 v11, v11, v11
	v_min_f32_e32 v3, v3, v11
	ds_bpermute_b32 v11, v6, v2
	s_waitcnt lgkmcnt(0)
	v_max_f32_e32 v11, v11, v11
	v_max_f32_e32 v2, v2, v11
	ds_bpermute_b32 v11, v6, v3
	s_waitcnt lgkmcnt(0)
	v_max_f32_e32 v11, v11, v11
	v_min_f32_e32 v3, v3, v11
	ds_bpermute_b32 v11, v5, v2
	s_waitcnt lgkmcnt(0)
	v_max_f32_e32 v11, v11, v11
	v_max_f32_e32 v2, v2, v11
	ds_bpermute_b32 v11, v5, v3
	s_waitcnt lgkmcnt(0)
	v_max_f32_e32 v11, v11, v11
	v_min_f32_e32 v3, v3, v11
	ds_bpermute_b32 v11, v0, v2
	s_waitcnt lgkmcnt(0)
	v_max_f32_e32 v11, v11, v11
	v_max_f32_e32 v2, v2, v11
	ds_bpermute_b32 v11, v0, v3
	s_waitcnt lgkmcnt(0)
	v_max_f32_e32 v11, v11, v11
	v_min_f32_e32 v11, v3, v11
	ds_bpermute_b32 v3, v4, v2
	ds_bpermute_b32 v12, v4, v11
	s_and_saveexec_b64 s[2:3], s[66:67]
	s_cbranch_execz .LBB0_329
	s_waitcnt lgkmcnt(0)
	v_max_f32_e32 v12, v12, v12
	v_max_f32_e32 v11, v11, v11
	v_max_f32_e32 v3, v3, v3
	v_max_f32_e32 v2, v2, v2
	v_min_f32_e32 v11, v11, v12
	v_max_f32_e32 v2, v2, v3
	v_sub_f32_e32 v3, v2, v11
	v_fmamk_f32 v3, v3, 0x3fb8aa3b, v10
	v_readlane_b32 s6, v254, 8
	v_cmp_gt_f32_e32 vcc, s24, v3
	v_fmamk_f32 v2, v2, 0x3fb8aa3b, v9
	v_mov_b32_e32 v11, s6
	v_readlane_b32 s6, v254, 9
	v_cndmask_b32_e64 v3, 0, 1.0, vcc
	ds_write_b32 v11, v2
	v_mov_b32_e32 v2, s6
	ds_write_b32 v2, v3

; __device__ __forceinline__ void attn_phase(const AttnArgs& A, GAS unsigned* counters, LAS unsigned char* lds) {
;     ...
;         for (int hc = 0; hc < 8; ++hc) { float bmx = -3.0e38f, bmn = 3.0e38f;
;             for (int j = ln; j < 257; j += 64) { const float v = A.rel_bias[hc * 257 + j]; bmx = fmaxf(bmx, v); bmn = fminf(bmn, v); }
; #pragma unroll
;             for (int o_ = 1; o_ < 64; o_ <<= 1) { bmx = fmaxf(bmx, __shfl_xor(bmx, o_)); bmn = fminf(bmn, __shfl_xor(bmn, o_)); }
;             if (ln == 0) { prm[2 + hc] = M0c + bmx * LOG2E; prm[10 + hc] = (2.0f * M0c + (bmx - bmn) * LOG2E < 100.0f) ? 1.0f : 0.0f; } }
.LBB0_330:
	v_max_f32_e32 v14, v206, v206
	v_max_f32_e32 v13, v13, v14
	v_min_f32_e32 v11, v11, v14
	v_max_f32_e32 v14, v207, v207
	v_max_f32_e32 v13, v13, v14
	v_min_f32_e32 v11, v11, v14
	v_max_f32_e32 v14, v208, v208
	v_max_f32_e32 v13, v13, v14
	v_min_f32_e32 v11, v11, v14
	v_max_f32_e32 v14, v209, v209
	v_max_f32_e32 v13, v13, v14
	v_min_f32_e32 v11, v11, v14
	v_max_f32_e32 v14, v210, v210
	v_max_f32_e32 v13, v13, v14
	v_min_f32_e32 v11, v11, v14
	s_or_b64 exec, exec, s[2:3]
	ds_bpermute_b32 v2, v8, v13
	v_max_f32_e32 v3, v13, v13
	s_waitcnt lgkmcnt(0)
	v_max_f32_e32 v2, v2, v2
	v_max_f32_e32 v2, v3, v2
	ds_bpermute_b32 v3, v8, v11
	v_max_f32_e32 v11, v11, v11
	s_waitcnt lgkmcnt(0)
	v_max_f32_e32 v3, v3, v3
	v_min_f32_e32 v3, v11, v3
	ds_bpermute_b32 v11, v7, v2
	s_waitcnt lgkmcnt(0)
	v_max_f32_e32 v11, v11, v11
	v_max_f32_e32 v2, v2, v11
	ds_bpermute_b32 v11, v7, v3
	s_waitcnt lgkmcnt(0)
	v_max_f32_e32 v11, v11, v11
	v_min_f32_e32 v3, v3, v11
	ds_bpermute_b32 v11, v6, v2
	s_waitcnt lgkmcnt(0)
	v_max_f32_e32 v11, v11, v11
	v_max_f32_e32 v2, v2, v11
	ds_bpermute_b32 v11, v6, v3
	s_waitcnt lgkmcnt(0)
	v_max_f32_e32 v11, v11, v11
	v_min_f32_e32 v3, v3, v11
	ds_bpermute_b32 v11, v5, v2
	s_waitcnt lgkmcnt(0)
	v_max_f32_e32 v11, v11, v11
	v_max_f32_e32 v2, v2, v11
	ds_bpermute_b32 v11, v5, v3
	s_waitcnt lgkmcnt(0)
	v_max_f32_e32 v11, v11, v11
	v_min_f32_e32 v3, v3, v11
	ds_bpermute_b32 v11, v0, v2
	s_waitcnt lgkmcnt(0)
	v_max_f32_e32 v11, v11, v11
	v_max_f32_e32 v2, v2, v11
	ds_bpermute_b32 v11, v0, v3
	s_waitcnt lgkmcnt(0)
	v_max_f32_e32 v11, v11, v11
	v_min_f32_e32 v11, v3, v11
	ds_bpermute_b32 v3, v4, v2
	ds_bpermute_b32 v12, v4, v11
	s_and_saveexec_b64 s[2:3], s[66:67]
	s_cbranch_execz .LBB0_333
	s_waitcnt lgkmcnt(0)
	v_max_f32_e32 v12, v12, v12
	v_max_f32_e32 v11, v11, v11
	v_max_f32_e32 v3, v3, v3
	v_max_f32_e32 v2, v2, v2
	v_min_f32_e32 v11, v11, v12
	v_max_f32_e32 v2, v2, v3
	v_sub_f32_e32 v3, v2, v11
	v_fmamk_f32 v3, v3, 0x3fb8aa3b, v10
	v_readlane_b32 s6, v254, 10
	v_cmp_gt_f32_e32 vcc, s24, v3
	v_fmamk_f32 v2, v2, 0x3fb8aa3b, v9
	v_mov_b32_e32 v11, s6
	v_readlane_b32 s6, v254, 11
	v_cndmask_b32_e64 v3, 0, 1.0, vcc
	ds_write_b32 v11, v2
	v_mov_b32_e32 v2, s6
	ds_write_b32 v2, v3

; __device__ __forceinline__ void attn_phase(const AttnArgs& A, GAS unsigned* counters, LAS unsigned char* lds) {
;     ...
;         for (int hc = 0; hc < 8; ++hc) { float bmx = -3.0e38f, bmn = 3.0e38f;
;             for (int j = ln; j < 257; j += 64) { const float v = A.rel_bias[hc * 257 + j]; bmx = fmaxf(bmx, v); bmn = fminf(bmn, v); }
; #pragma unroll
;             for (int o_ = 1; o_ < 64; o_ <<= 1) { bmx = fmaxf(bmx, __shfl_xor(bmx, o_)); bmn = fminf(bmn, __shfl_xor(bmn, o_)); }
;             if (ln == 0) { prm[2 + hc] = M0c + bmx * LOG2E; prm[10 + hc] = (2.0f * M0c + (bmx - bmn) * LOG2E < 100.0f) ? 1.0f : 0.0f; } }
.LBB0_334:
	v_max_f32_e32 v14, v211, v211
	v_max_f32_e32 v13, v13, v14
	v_min_f32_e32 v11, v11, v14
	v_max_f32_e32 v14, v212, v212
	v_max_f32_e32 v13, v13, v14
	v_min_f32_e32 v11, v11, v14
	v_max_f32_e32 v14, v213, v213
	v_max_f32_e32 v13, v13, v14
	v_min_f32_e32 v11, v11, v14
	v_max_f32_e32 v14, v214, v214
	v_max_f32_e32 v13, v13, v14
	v_min_f32_e32 v11, v11, v14
	v_max_f32_e32 v14, v215, v215
	v_max_f32_e32 v13, v13, v14
	v_min_f32_e32 v11, v11, v14
	s_or_b64 exec, exec, s[2:3]
	ds_bpermute_b32 v2, v8, v13
	v_max_f32_e32 v3, v13, v13
	s_waitcnt lgkmcnt(0)
	v_max_f32_e32 v2, v2, v2
	v_max_f32_e32 v2, v3, v2
	ds_bpermute_b32 v3, v8, v11
	v_max_f32_e32 v11, v11, v11
	s_waitcnt lgkmcnt(0)
	v_max_f32_e32 v3, v3, v3
	v_min_f32_e32 v3, v11, v3
	ds_bpermute_b32 v11, v7, v2
	s_waitcnt lgkmcnt(0)
	v_max_f32_e32 v11, v11, v11
	v_max_f32_e32 v2, v2, v11
	ds_bpermute_b32 v11, v7, v3
	s_waitcnt lgkmcnt(0)
	v_max_f32_e32 v11, v11, v11
	v_min_f32_e32 v3, v3, v11
	ds_bpermute_b32 v11, v6, v2
	s_waitcnt lgkmcnt(0)
	v_max_f32_e32 v11, v11, v11
	v_max_f32_e32 v2, v2, v11
	ds_bpermute_b32 v11, v6, v3
	s_waitcnt lgkmcnt(0)
	v_max_f32_e32 v11, v11, v11
	v_min_f32_e32 v3, v3, v11
	ds_bpermute_b32 v11, v5, v2
	s_waitcnt lgkmcnt(0)
	v_max_f32_e32 v11, v11, v11
	v_max_f32_e32 v2, v2, v11
	ds_bpermute_b32 v11, v5, v3
	s_waitcnt lgkmcnt(0)
	v_max_f32_e32 v11, v11, v11
	v_min_f32_e32 v3, v3, v11
	ds_bpermute_b32 v11, v0, v2
	s_waitcnt lgkmcnt(0)
	v_max_f32_e32 v11, v11, v11
	v_max_f32_e32 v2, v2, v11
	ds_bpermute_b32 v11, v0, v3
	s_waitcnt lgkmcnt(0)
	v_max_f32_e32 v11, v11, v11
	v_min_f32_e32 v11, v3, v11
	ds_bpermute_b32 v3, v4, v2
	ds_bpermute_b32 v12, v4, v11
	s_and_saveexec_b64 s[2:3], s[66:67]
	s_cbranch_execz .LBB0_337
	s_waitcnt lgkmcnt(0)
	v_max_f32_e32 v12, v12, v12
	v_max_f32_e32 v11, v11, v11
	v_max_f32_e32 v3, v3, v3
	v_max_f32_e32 v2, v2, v2
	v_min_f32_e32 v11, v11, v12
	v_max_f32_e32 v2, v2, v3
	v_sub_f32_e32 v3, v2, v11
	v_fmamk_f32 v3, v3, 0x3fb8aa3b, v10
	v_readlane_b32 s6, v254, 12
	v_cmp_gt_f32_e32 vcc, s24, v3
	v_fmamk_f32 v2, v2, 0x3fb8aa3b, v9
	v_mov_b32_e32 v11, s6
	v_readlane_b32 s6, v254, 13
	v_cndmask_b32_e64 v3, 0, 1.0, vcc
	ds_write_b32 v11, v2
	v_mov_b32_e32 v2, s6
	ds_write_b32 v2, v3

; __device__ __forceinline__ void attn_phase(const AttnArgs& A, GAS unsigned* counters, LAS unsigned char* lds) {
;     ...
;         for (int hc = 0; hc < 8; ++hc) { float bmx = -3.0e38f, bmn = 3.0e38f;
;             for (int j = ln; j < 257; j += 64) { const float v = A.rel_bias[hc * 257 + j]; bmx = fmaxf(bmx, v); bmn = fminf(bmn, v); }
; #pragma unroll
;             for (int o_ = 1; o_ < 64; o_ <<= 1) { bmx = fmaxf(bmx, __shfl_xor(bmx, o_)); bmn = fminf(bmn, __shfl_xor(bmn, o_)); }
;             if (ln == 0) { prm[2 + hc] = M0c + bmx * LOG2E; prm[10 + hc] = (2.0f * M0c + (bmx - bmn) * LOG2E < 100.0f) ? 1.0f : 0.0f; } }
.LBB0_338:
	v_max_f32_e32 v14, v216, v216
	v_max_f32_e32 v13, v13, v14
	v_min_f32_e32 v11, v11, v14
	v_max_f32_e32 v14, v217, v217
	v_max_f32_e32 v13, v13, v14
	v_min_f32_e32 v11, v11, v14
	v_max_f32_e32 v14, v218, v218
	v_max_f32_e32 v13, v13, v14
	v_min_f32_e32 v11, v11, v14
	v_max_f32_e32 v14, v219, v219
	v_max_f32_e32 v13, v13, v14
	v_min_f32_e32 v11, v11, v14
	v_max_f32_e32 v14, v220, v220
	v_max_f32_e32 v13, v13, v14
	v_min_f32_e32 v11, v11, v14
	s_or_b64 exec, exec, s[2:3]
	ds_bpermute_b32 v2, v8, v13
	v_max_f32_e32 v3, v13, v13
	s_waitcnt lgkmcnt(0)
	v_max_f32_e32 v2, v2, v2
	v_max_f32_e32 v2, v3, v2
	ds_bpermute_b32 v3, v8, v11
	v_max_f32_e32 v11, v11, v11
	s_waitcnt lgkmcnt(0)
	v_max_f32_e32 v3, v3, v3
	v_min_f32_e32 v3, v11, v3
	ds_bpermute_b32 v11, v7, v2
	s_waitcnt lgkmcnt(0)
	v_max_f32_e32 v11, v11, v11
	v_max_f32_e32 v2, v2, v11
	ds_bpermute_b32 v11, v7, v3
	s_waitcnt lgkmcnt(0)
	v_max_f32_e32 v11, v11, v11
	v_min_f32_e32 v3, v3, v11
	ds_bpermute_b32 v11, v6, v2
	s_waitcnt lgkmcnt(0)
	v_max_f32_e32 v11, v11, v11
	v_max_f32_e32 v2, v2, v11
	ds_bpermute_b32 v11, v6, v3
	s_waitcnt lgkmcnt(0)
	v_max_f32_e32 v11, v11, v11
	v_min_f32_e32 v3, v3, v11
	ds_bpermute_b32 v11, v5, v2
	s_waitcnt lgkmcnt(0)
	v_max_f32_e32 v11, v11, v11
	v_max_f32_e32 v2, v2, v11
	ds_bpermute_b32 v11, v5, v3
	s_waitcnt lgkmcnt(0)
	v_max_f32_e32 v11, v11, v11
	v_min_f32_e32 v3, v3, v11
	ds_bpermute_b32 v11, v0, v2
	s_waitcnt lgkmcnt(0)
	v_max_f32_e32 v11, v11, v11
	v_max_f32_e32 v2, v2, v11
	ds_bpermute_b32 v11, v0, v3
	s_waitcnt lgkmcnt(0)
	v_max_f32_e32 v11, v11, v11
	v_min_f32_e32 v11, v3, v11
	ds_bpermute_b32 v3, v4, v2
	ds_bpermute_b32 v12, v4, v11
	s_and_saveexec_b64 s[2:3], s[66:67]
	s_cbranch_execz .LBB0_341
	s_waitcnt lgkmcnt(0)
	v_max_f32_e32 v12, v12, v12
	v_max_f32_e32 v11, v11, v11
	v_max_f32_e32 v3, v3, v3
	v_max_f32_e32 v2, v2, v2
	v_min_f32_e32 v11, v11, v12
	v_max_f32_e32 v2, v2, v3
	v_sub_f32_e32 v3, v2, v11
	v_fmamk_f32 v3, v3, 0x3fb8aa3b, v10
	v_readlane_b32 s6, v254, 14
	v_cmp_gt_f32_e32 vcc, s24, v3
	v_fmamk_f32 v2, v2, 0x3fb8aa3b, v9
	v_mov_b32_e32 v11, s6
	v_readlane_b32 s6, v254, 15
	v_cndmask_b32_e64 v3, 0, 1.0, vcc
	ds_write_b32 v11, v2
	v_mov_b32_e32 v2, s6
	ds_write_b32 v2, v3

; __device__ __forceinline__ void attn_phase(const AttnArgs& A, GAS unsigned* counters, LAS unsigned char* lds) {
;     ...
;         for (int hc = 0; hc < 8; ++hc) { float bmx = -3.0e38f, bmn = 3.0e38f;
;             for (int j = ln; j < 257; j += 64) { const float v = A.rel_bias[hc * 257 + j]; bmx = fmaxf(bmx, v); bmn = fminf(bmn, v); }
; #pragma unroll
;             for (int o_ = 1; o_ < 64; o_ <<= 1) { bmx = fmaxf(bmx, __shfl_xor(bmx, o_)); bmn = fminf(bmn, __shfl_xor(bmn, o_)); }
;             if (ln == 0) { prm[2 + hc] = M0c + bmx * LOG2E; prm[10 + hc] = (2.0f * M0c + (bmx - bmn) * LOG2E < 100.0f) ? 1.0f : 0.0f; } }
.LBB0_342:
	v_max_f32_e32 v14, v221, v221
	v_max_f32_e32 v12, v12, v14
	v_min_f32_e32 v11, v11, v14
	v_max_f32_e32 v14, v222, v222
	v_max_f32_e32 v12, v12, v14
	v_min_f32_e32 v11, v11, v14
	v_max_f32_e32 v14, v223, v223
	v_max_f32_e32 v12, v12, v14
	v_min_f32_e32 v11, v11, v14
	v_max_f32_e32 v14, v224, v224
	v_max_f32_e32 v12, v12, v14
	v_min_f32_e32 v11, v11, v14
	v_max_f32_e32 v14, v225, v225
	v_max_f32_e32 v12, v12, v14
	v_min_f32_e32 v11, v11, v14
	s_or_b64 exec, exec, s[2:3]
	ds_bpermute_b32 v2, v8, v12
	ds_bpermute_b32 v3, v8, v11
	v_max_f32_e32 v8, v12, v12
	v_max_f32_e32 v11, v11, v11
	s_waitcnt lgkmcnt(1)
	v_max_f32_e32 v2, v2, v2
	s_waitcnt lgkmcnt(0)
	v_max_f32_e32 v3, v3, v3
	v_max_f32_e32 v2, v8, v2
	v_min_f32_e32 v3, v11, v3
	ds_bpermute_b32 v8, v7, v2
	ds_bpermute_b32 v7, v7, v3
	s_waitcnt lgkmcnt(1)
	v_max_f32_e32 v8, v8, v8
	s_waitcnt lgkmcnt(0)
	v_max_f32_e32 v7, v7, v7
	v_max_f32_e32 v2, v2, v8
	v_min_f32_e32 v3, v3, v7
	ds_bpermute_b32 v7, v6, v2
	ds_bpermute_b32 v6, v6, v3
	s_waitcnt lgkmcnt(1)
	v_max_f32_e32 v7, v7, v7
	s_waitcnt lgkmcnt(0)
	v_max_f32_e32 v6, v6, v6
	v_max_f32_e32 v2, v2, v7
	v_min_f32_e32 v3, v3, v6
	ds_bpermute_b32 v6, v5, v2
	ds_bpermute_b32 v5, v5, v3
	s_waitcnt lgkmcnt(1)
	v_max_f32_e32 v6, v6, v6
	s_waitcnt lgkmcnt(0)
	v_max_f32_e32 v5, v5, v5
	v_max_f32_e32 v2, v2, v6
	v_min_f32_e32 v3, v3, v5
	ds_bpermute_b32 v5, v0, v2
	ds_bpermute_b32 v0, v0, v3
	s_waitcnt lgkmcnt(1)
	v_max_f32_e32 v5, v5, v5
	s_waitcnt lgkmcnt(0)
	v_max_f32_e32 v6, v0, v0
	v_max_f32_e32 v0, v2, v5
	v_min_f32_e32 v3, v3, v6
	ds_bpermute_b32 v2, v4, v0
	ds_bpermute_b32 v4, v4, v3
	s_and_b64 exec, exec, s[66:67]
	s_cbranch_execz .LBB0_345
	s_waitcnt lgkmcnt(0)
	v_max_f32_e32 v4, v4, v4
	v_max_f32_e32 v3, v3, v3
	v_max_f32_e32 v2, v2, v2
	v_max_f32_e32 v0, v0, v0
	v_min_f32_e32 v3, v3, v4
	v_max_f32_e32 v0, v0, v2
	v_sub_f32_e32 v2, v0, v3
	v_fmac_f32_e32 v10, 0x3fb8aa3b, v2
	v_readlane_b32 s2, v254, 16
	v_cmp_gt_f32_e32 vcc, s24, v10
	v_fmac_f32_e32 v9, 0x3fb8aa3b, v0
	v_mov_b32_e32 v0, s2
	v_readlane_b32 s2, v254, 17
	v_cndmask_b32_e64 v2, 0, 1.0, vcc
	ds_write_b32 v0, v9
	v_mov_b32_e32 v0, s2
	ds_write_b32 v0, v2
